# v20 plus: back-edge bookkeeping of the down and w_out K-loops also moved into the preceding load segment
# speedup vs baseline: 1.0134x; 1.0019x over previous
; #define PG8_STAGE(bufoff, gbase, voff) do { _Pragma("unroll") for (int _i = 0; _i < 2; ++_i) \
;         __builtin_amdgcn_global_load_lds((const unsigned*)((const char*)(gbase) + (voff)[_i]), (LAS unsigned*)(lds + (bufoff) + ldsw + _i * 8192), 16, 0, 0); } while (0)
; #define PG8_LDA(dst, b, h) do { _Pragma("unroll") for (int m = 0; m < 4; ++m) _Pragma("unroll") for (int k = 0; k < 2; ++k) dst[m][k] = *(const LAS bf16x8*)(lds + PG8_SA(b, h) + aoff + m * 2048 + k * 1024); } while (0)
; #define PG8_LDB(dst, b, h) do { _Pragma("unroll") for (int n = 0; n < 2; ++n) _Pragma("unroll") for (int k = 0; k < 2; ++k) dst[n][k] = *(const LAS bf16x8*)(lds + PG8_SB(b, h) + boff + n * 2048 + k * 1024); } while (0)
; #define PG8_MMA(ai, bj, At, Bt) do { __builtin_amdgcn_s_setprio(1); _Pragma("unroll") for (int m = 0; m < 4; ++m) _Pragma("unroll") for (int n = 0; n < 2; ++n) _Pragma("unroll") for (int k = 0; k < 2; ++k) \
;         acc[ai][bj][m][n] = __builtin_amdgcn_mfma_f32_16x16x32_bf16(Bt[n][k], At[m][k], acc[ai][bj][m][n], 0, 0, 0); __builtin_amdgcn_s_setprio(0); } while (0)
; #define PG8_WAIT_V(n) asm volatile("s_waitcnt vmcnt(" #n ")" ::: "memory")
; #define PG8_WAIT_L(n) asm volatile("s_waitcnt lgkmcnt(" #n ")" ::: "memory")
; template <class Epi, class Sched>
; __device__ __forceinline__ void gemm_phase(LAS unsigned char* lds, const Gemm g, const Sched& S, const Epi& E) {
;     ...
;         for (int t = 0; t < nt; t += 2) {
;             const bool last = (t == nt - 2);
;             const char* a1 = cA + (size_t)(t + 1) * kstep;
;             const char* a2 = last ? nA : cA + (size_t)(t + 2) * kstep; const char* b2 = last ? nB : cB + (size_t)(t + 2) * kstep;
;             const char* a3 = a2 + kstep; const char* b3 = b2 + kstep;
;             PG8_LDB(B0, 0, 0); PG8_SCHED; PG8_LDA(At, 0, 0); PG8_STAGE(PG8_SA(1, 1), a1 + hstep, voffA);
;             PG8_WAIT_L(8); PG8_BAR; PG8_WAIT_L(0); PG8_MMA(0, 0, At, B0); PG8_BAR; PG8_SCHED;
;             PG8_LDB(B1, 0, 1); PG8_STAGE(PG8_SB(0, 0), b2, voffB);
;             PG8_BAR; PG8_WAIT_L(0); PG8_MMA(0, 1, At, B1); PG8_BAR;
;             PG8_LDA(At, 0, 1); PG8_STAGE(PG8_SA(0, 0), a2, voffA);
;             PG8_BAR; PG8_WAIT_L(0); PG8_MMA(1, 0, At, B0); PG8_BAR; PG8_SCHED;
;             PG8_STAGE(PG8_SB(0, 1), b2 + hstep, voffB);
;             PG8_WAIT_V(6); PG8_BAR; PG8_MMA(1, 1, At, B1); PG8_BAR;
.LBB0_170:
	s_add_i32 s53, s22, 2
	s_add_u32 s20, s16, 0x100
	s_addc_u32 s21, s17, 0
	s_add_i32 s54, 0, 0x10000
	ds_read_b128 v[128:131], v141
	ds_read_b128 v[132:135], v141 offset:1024
	ds_read_b128 v[136:139], v141 offset:2048
	ds_read_b128 v[160:163], v141 offset:3072
	s_cmp_eq_u32 s15, s22
	s_cselect_b32 s22, s4, s51
	s_cselect_b32 s25, s7, s21
	s_cselect_b32 s24, s6, s20
	s_cselect_b32 s23, s5, s52
	s_add_i32 m0, s35, 0xc000
	ds_read_b128 v[164:167], v173
	ds_read_b128 v[174:177], v173 offset:1024
	ds_read_b128 v[200:203], v173 offset:2048
	ds_read_b128 v[204:207], v173 offset:3072
	ds_read_b128 v[208:211], v173 offset:4096
	ds_read_b128 v[212:215], v173 offset:5120
	ds_read_b128 v[216:219], v173 offset:6144
	ds_read_b128 v[220:223], v173 offset:7168
	global_load_lds_dwordx4 v142, s[16:17]
	s_add_i32 m0, s35, 0xe000
	s_nop 0
	global_load_lds_dwordx4 v144, s[16:17]
	s_waitcnt lgkmcnt(8)
	s_barrier
	s_waitcnt lgkmcnt(0)
	v_mfma_f32_16x16x32_bf16 v[124:127], v[128:131], v[164:167], v[124:127]
	v_mfma_f32_16x16x32_bf16 v[120:123], v[136:139], v[164:167], v[120:123]
	v_mfma_f32_16x16x32_bf16 v[116:119], v[128:131], v[200:203], v[116:119]
	v_mfma_f32_16x16x32_bf16 v[112:115], v[136:139], v[200:203], v[112:115]
	v_mfma_f32_16x16x32_bf16 v[100:103], v[128:131], v[208:211], v[100:103]
	v_mfma_f32_16x16x32_bf16 v[96:99], v[136:139], v[208:211], v[96:99]
	v_mfma_f32_16x16x32_bf16 v[84:87], v[128:131], v[216:219], v[84:87]
	v_mfma_f32_16x16x32_bf16 v[80:83], v[136:139], v[216:219], v[80:83]
	v_mfma_f32_16x16x32_bf16 v[124:127], v[132:135], v[174:177], v[124:127]
	v_mfma_f32_16x16x32_bf16 v[120:123], v[160:163], v[174:177], v[120:123]
	v_mfma_f32_16x16x32_bf16 v[116:119], v[132:135], v[204:207], v[116:119]
	v_mfma_f32_16x16x32_bf16 v[112:115], v[160:163], v[204:207], v[112:115]
	v_mfma_f32_16x16x32_bf16 v[100:103], v[132:135], v[212:215], v[100:103]
	v_mfma_f32_16x16x32_bf16 v[96:99], v[160:163], v[212:215], v[96:99]
	v_mfma_f32_16x16x32_bf16 v[84:87], v[132:135], v[220:223], v[84:87]
	v_mfma_f32_16x16x32_bf16 v[80:83], v[160:163], v[220:223], v[80:83]
	s_barrier
	s_add_i32 s55, 0, 0x14000
	s_add_i32 s16, s54, s29
	ds_read_b128 v[224:227], v141 offset:16384
	ds_read_b128 v[228:231], v141 offset:17408
	ds_read_b128 v[232:235], v141 offset:18432
	ds_read_b128 v[236:239], v141 offset:19456
	s_add_u32 s84, s22, 0x80
	s_addc_u32 s85, s23, 0
	s_mov_b32 m0, s16
	s_nop 0
	global_load_lds_dwordx4 v148, s[22:23]
	s_add_i32 m0, s16, 0x2000
	s_nop 0
	global_load_lds_dwordx4 v140, s[22:23]
	s_barrier
	s_waitcnt lgkmcnt(0)
	v_mfma_f32_16x16x32_bf16 v[108:111], v[224:227], v[164:167], v[108:111]
	v_mfma_f32_16x16x32_bf16 v[104:107], v[232:235], v[164:167], v[104:107]
	v_mfma_f32_16x16x32_bf16 v[92:95], v[224:227], v[200:203], v[92:95]
	v_mfma_f32_16x16x32_bf16 v[88:91], v[232:235], v[200:203], v[88:91]
	v_mfma_f32_16x16x32_bf16 v[76:79], v[224:227], v[208:211], v[76:79]
	v_mfma_f32_16x16x32_bf16 v[72:75], v[232:235], v[208:211], v[72:75]
	v_mfma_f32_16x16x32_bf16 v[68:71], v[224:227], v[216:219], v[68:71]
	v_mfma_f32_16x16x32_bf16 v[64:67], v[232:235], v[216:219], v[64:67]
	v_mfma_f32_16x16x32_bf16 v[108:111], v[228:231], v[174:177], v[108:111]
	v_mfma_f32_16x16x32_bf16 v[104:107], v[236:239], v[174:177], v[104:107]
	v_mfma_f32_16x16x32_bf16 v[92:95], v[228:231], v[204:207], v[92:95]
	v_mfma_f32_16x16x32_bf16 v[88:91], v[236:239], v[204:207], v[88:91]
	v_mfma_f32_16x16x32_bf16 v[76:79], v[228:231], v[212:215], v[76:79]
	v_mfma_f32_16x16x32_bf16 v[72:75], v[236:239], v[212:215], v[72:75]
	v_mfma_f32_16x16x32_bf16 v[68:71], v[228:231], v[220:223], v[68:71]
	v_mfma_f32_16x16x32_bf16 v[64:67], v[236:239], v[220:223], v[64:67]
	s_barrier
	s_mov_b32 m0, s35
	s_add_u32 s86, s24, 0x80
	s_addc_u32 s87, s25, 0
	ds_read_b128 v[164:167], v173 offset:16384
	ds_read_b128 v[174:177], v173 offset:17408
	ds_read_b128 v[200:203], v173 offset:18432
	ds_read_b128 v[204:207], v173 offset:19456
	ds_read_b128 v[208:211], v173 offset:20480
	ds_read_b128 v[212:215], v173 offset:21504
	ds_read_b128 v[216:219], v173 offset:22528
	ds_read_b128 v[220:223], v173 offset:23552
	global_load_lds_dwordx4 v148, s[24:25]
	s_mov_b32 m0, s36
	s_nop 0
	global_load_lds_dwordx4 v140, s[24:25]
	s_barrier
	s_waitcnt lgkmcnt(0)
	v_mfma_f32_16x16x32_bf16 v[60:63], v[128:131], v[164:167], v[60:63]
	v_mfma_f32_16x16x32_bf16 v[56:59], v[136:139], v[164:167], v[56:59]
	v_mfma_f32_16x16x32_bf16 v[52:55], v[128:131], v[200:203], v[52:55]
	v_mfma_f32_16x16x32_bf16 v[48:51], v[136:139], v[200:203], v[48:51]
	v_mfma_f32_16x16x32_bf16 v[36:39], v[128:131], v[208:211], v[36:39]
	v_mfma_f32_16x16x32_bf16 v[32:35], v[136:139], v[208:211], v[32:35]
	v_mfma_f32_16x16x32_bf16 v[20:23], v[128:131], v[216:219], v[20:23]
	v_mfma_f32_16x16x32_bf16 v[16:19], v[136:139], v[216:219], v[16:19]
	v_mfma_f32_16x16x32_bf16 v[60:63], v[132:135], v[174:177], v[60:63]
	v_mfma_f32_16x16x32_bf16 v[56:59], v[160:163], v[174:177], v[56:59]
	v_mfma_f32_16x16x32_bf16 v[52:55], v[132:135], v[204:207], v[52:55]
	v_mfma_f32_16x16x32_bf16 v[48:51], v[160:163], v[204:207], v[48:51]
	v_mfma_f32_16x16x32_bf16 v[36:39], v[132:135], v[212:215], v[36:39]
	v_mfma_f32_16x16x32_bf16 v[32:35], v[160:163], v[212:215], v[32:35]
	v_mfma_f32_16x16x32_bf16 v[20:23], v[132:135], v[220:223], v[20:23]
	v_mfma_f32_16x16x32_bf16 v[16:19], v[160:163], v[220:223], v[16:19]
	s_barrier
	s_add_u32 s16, s22, 0x160000
	s_addc_u32 s17, s23, 0
	s_add_i32 s54, s55, s29
	s_mov_b32 m0, s54
	s_nop 0
	global_load_lds_dwordx4 v148, s[16:17]
	s_add_i32 m0, s54, 0x2000
	s_nop 0
	global_load_lds_dwordx4 v140, s[16:17]
	s_waitcnt vmcnt(6)
	s_barrier
; #define PG8_STAGE(bufoff, gbase, voff) do { _Pragma("unroll") for (int _i = 0; _i < 2; ++_i) \
;         __builtin_amdgcn_global_load_lds((const unsigned*)((const char*)(gbase) + (voff)[_i]), (LAS unsigned*)(lds + (bufoff) + ldsw + _i * 8192), 16, 0, 0); } while (0)
; #define PG8_LDA(dst, b, h) do { _Pragma("unroll") for (int m = 0; m < 4; ++m) _Pragma("unroll") for (int k = 0; k < 2; ++k) dst[m][k] = *(const LAS bf16x8*)(lds + PG8_SA(b, h) + aoff + m * 2048 + k * 1024); } while (0)
; #define PG8_LDB(dst, b, h) do { _Pragma("unroll") for (int n = 0; n < 2; ++n) _Pragma("unroll") for (int k = 0; k < 2; ++k) dst[n][k] = *(const LAS bf16x8*)(lds + PG8_SB(b, h) + boff + n * 2048 + k * 1024); } while (0)
; #define PG8_MMA(ai, bj, At, Bt) do { __builtin_amdgcn_s_setprio(1); _Pragma("unroll") for (int m = 0; m < 4; ++m) _Pragma("unroll") for (int n = 0; n < 2; ++n) _Pragma("unroll") for (int k = 0; k < 2; ++k) \
;         acc[ai][bj][m][n] = __builtin_amdgcn_mfma_f32_16x16x32_bf16(Bt[n][k], At[m][k], acc[ai][bj][m][n], 0, 0, 0); __builtin_amdgcn_s_setprio(0); } while (0)
; #define PG8_WAIT_V(n) asm volatile("s_waitcnt vmcnt(" #n ")" ::: "memory")
; #define PG8_WAIT_L(n) asm volatile("s_waitcnt lgkmcnt(" #n ")" ::: "memory")
; #define PG8_BAR __builtin_amdgcn_s_barrier()
; #define PG8_SCHED __builtin_amdgcn_sched_barrier(0)
; template <class Epi, class Sched>
; __device__ __forceinline__ void gemm_phase(LAS unsigned char* lds, const Gemm g, const Sched& S, const Epi& E) {
;     ...
;             PG8_WAIT_V(6); PG8_BAR; PG8_MMA(1, 1, At, B1); PG8_BAR;
;             PG8_LDB(B0, 1, 0); PG8_SCHED; PG8_LDA(At, 1, 0); PG8_STAGE(PG8_SA(0, 1), a2 + hstep, voffA);
;             PG8_WAIT_L(8); PG8_BAR; PG8_WAIT_L(0); PG8_MMA(0, 0, At, B0); PG8_BAR; PG8_SCHED;
;             PG8_LDB(B1, 1, 1); PG8_STAGE(PG8_SB(1, 0), b3, voffB);
;             PG8_BAR; PG8_WAIT_L(0); PG8_MMA(0, 1, At, B1); PG8_BAR;
;             PG8_LDA(At, 1, 1); PG8_STAGE(PG8_SA(1, 0), a3, voffA);
;             PG8_BAR; PG8_WAIT_L(0); PG8_MMA(1, 0, At, B0); PG8_BAR; PG8_SCHED;
	v_mfma_f32_16x16x32_bf16 v[44:47], v[224:227], v[164:167], v[44:47]
	v_mfma_f32_16x16x32_bf16 v[40:43], v[232:235], v[164:167], v[40:43]
	v_mfma_f32_16x16x32_bf16 v[28:31], v[224:227], v[200:203], v[28:31]
	v_mfma_f32_16x16x32_bf16 v[24:27], v[232:235], v[200:203], v[24:27]
	v_mfma_f32_16x16x32_bf16 v[12:15], v[224:227], v[208:211], v[12:15]
	v_mfma_f32_16x16x32_bf16 v[8:11], v[232:235], v[208:211], v[8:11]
	v_mfma_f32_16x16x32_bf16 v[4:7], v[224:227], v[216:219], v[4:7]
	v_mfma_f32_16x16x32_bf16 v[0:3], v[232:235], v[216:219], v[0:3]
	v_mfma_f32_16x16x32_bf16 v[44:47], v[228:231], v[174:177], v[44:47]
	v_mfma_f32_16x16x32_bf16 v[40:43], v[236:239], v[174:177], v[40:43]
	v_mfma_f32_16x16x32_bf16 v[28:31], v[228:231], v[204:207], v[28:31]
	v_mfma_f32_16x16x32_bf16 v[24:27], v[236:239], v[204:207], v[24:27]
	v_mfma_f32_16x16x32_bf16 v[12:15], v[228:231], v[212:215], v[12:15]
	v_mfma_f32_16x16x32_bf16 v[8:11], v[236:239], v[212:215], v[8:11]
	v_mfma_f32_16x16x32_bf16 v[4:7], v[228:231], v[220:223], v[4:7]
	v_mfma_f32_16x16x32_bf16 v[0:3], v[236:239], v[220:223], v[0:3]
	s_barrier
	s_add_i32 s54, 0, 0x18000
	ds_read_b128 v[128:131], v141 offset:32768
	ds_read_b128 v[132:135], v141 offset:33792
	ds_read_b128 v[136:139], v141 offset:34816
	ds_read_b128 v[160:163], v141 offset:35840
	s_add_u32 s16, s24, 0x160000
	s_addc_u32 s17, s25, 0
	s_mov_b32 m0, s37
	ds_read_b128 v[164:167], v173 offset:32768
	ds_read_b128 v[174:177], v173 offset:33792
	ds_read_b128 v[200:203], v173 offset:34816
	ds_read_b128 v[204:207], v173 offset:35840
	ds_read_b128 v[208:211], v173 offset:36864
	ds_read_b128 v[212:215], v173 offset:37888
	ds_read_b128 v[216:219], v173 offset:38912
	ds_read_b128 v[220:223], v173 offset:39936
	global_load_lds_dwordx4 v148, s[16:17]
	s_mov_b32 m0, s38
	s_nop 0
	global_load_lds_dwordx4 v140, s[16:17]
	s_waitcnt lgkmcnt(8)
	s_barrier
	s_waitcnt lgkmcnt(0)
	v_mfma_f32_16x16x32_bf16 v[124:127], v[128:131], v[164:167], v[124:127]
	v_mfma_f32_16x16x32_bf16 v[120:123], v[136:139], v[164:167], v[120:123]
	v_mfma_f32_16x16x32_bf16 v[116:119], v[128:131], v[200:203], v[116:119]
	v_mfma_f32_16x16x32_bf16 v[112:115], v[136:139], v[200:203], v[112:115]
	v_mfma_f32_16x16x32_bf16 v[100:103], v[128:131], v[208:211], v[100:103]
	v_mfma_f32_16x16x32_bf16 v[96:99], v[136:139], v[208:211], v[96:99]
	v_mfma_f32_16x16x32_bf16 v[84:87], v[128:131], v[216:219], v[84:87]
	v_mfma_f32_16x16x32_bf16 v[80:83], v[136:139], v[216:219], v[80:83]
	v_mfma_f32_16x16x32_bf16 v[124:127], v[132:135], v[174:177], v[124:127]
	v_mfma_f32_16x16x32_bf16 v[120:123], v[160:163], v[174:177], v[120:123]
	v_mfma_f32_16x16x32_bf16 v[116:119], v[132:135], v[204:207], v[116:119]
	v_mfma_f32_16x16x32_bf16 v[112:115], v[160:163], v[204:207], v[112:115]
	v_mfma_f32_16x16x32_bf16 v[100:103], v[132:135], v[212:215], v[100:103]
	v_mfma_f32_16x16x32_bf16 v[96:99], v[160:163], v[212:215], v[96:99]
	v_mfma_f32_16x16x32_bf16 v[84:87], v[132:135], v[220:223], v[84:87]
	v_mfma_f32_16x16x32_bf16 v[80:83], v[160:163], v[220:223], v[80:83]
	s_barrier
	s_add_i32 s24, 0, 0x1c000
	s_add_i32 s16, s54, s29
	s_mov_b32 m0, s16
	ds_read_b128 v[224:227], v141 offset:49152
	ds_read_b128 v[228:231], v141 offset:50176
	ds_read_b128 v[232:235], v141 offset:51200
	ds_read_b128 v[236:239], v141 offset:52224
	global_load_lds_dwordx4 v148, s[84:85]
	s_add_i32 m0, s16, 0x2000
	s_nop 0
	global_load_lds_dwordx4 v140, s[84:85]
	s_barrier
	s_waitcnt lgkmcnt(0)
	v_mfma_f32_16x16x32_bf16 v[108:111], v[224:227], v[164:167], v[108:111]
	v_mfma_f32_16x16x32_bf16 v[104:107], v[232:235], v[164:167], v[104:107]
	v_mfma_f32_16x16x32_bf16 v[92:95], v[224:227], v[200:203], v[92:95]
	v_mfma_f32_16x16x32_bf16 v[88:91], v[232:235], v[200:203], v[88:91]
	v_mfma_f32_16x16x32_bf16 v[76:79], v[224:227], v[208:211], v[76:79]
	v_mfma_f32_16x16x32_bf16 v[72:75], v[232:235], v[208:211], v[72:75]
	v_mfma_f32_16x16x32_bf16 v[68:71], v[224:227], v[216:219], v[68:71]
	v_mfma_f32_16x16x32_bf16 v[64:67], v[232:235], v[216:219], v[64:67]
	v_mfma_f32_16x16x32_bf16 v[108:111], v[228:231], v[174:177], v[108:111]
	v_mfma_f32_16x16x32_bf16 v[104:107], v[236:239], v[174:177], v[104:107]
	v_mfma_f32_16x16x32_bf16 v[92:95], v[228:231], v[204:207], v[92:95]
	v_mfma_f32_16x16x32_bf16 v[88:91], v[236:239], v[204:207], v[88:91]
	v_mfma_f32_16x16x32_bf16 v[76:79], v[228:231], v[212:215], v[76:79]
	v_mfma_f32_16x16x32_bf16 v[72:75], v[236:239], v[212:215], v[72:75]
	v_mfma_f32_16x16x32_bf16 v[68:71], v[228:231], v[220:223], v[68:71]
	v_mfma_f32_16x16x32_bf16 v[64:67], v[236:239], v[220:223], v[64:67]
	s_barrier
	s_mov_b32 m0, s41
	ds_read_b128 v[164:167], v173 offset:49152
	ds_read_b128 v[174:177], v173 offset:50176
	ds_read_b128 v[200:203], v173 offset:51200
	ds_read_b128 v[204:207], v173 offset:52224
	ds_read_b128 v[208:211], v173 offset:53248
	ds_read_b128 v[212:215], v173 offset:54272
	ds_read_b128 v[216:219], v173 offset:55296
	ds_read_b128 v[220:223], v173 offset:56320
	global_load_lds_dwordx4 v148, s[86:87]
	s_mov_b32 m0, s42
	s_nop 0
	global_load_lds_dwordx4 v140, s[86:87]
	s_barrier
	s_waitcnt lgkmcnt(0)
	v_mfma_f32_16x16x32_bf16 v[60:63], v[128:131], v[164:167], v[60:63]
	v_mfma_f32_16x16x32_bf16 v[56:59], v[136:139], v[164:167], v[56:59]
	v_mfma_f32_16x16x32_bf16 v[52:55], v[128:131], v[200:203], v[52:55]
	v_mfma_f32_16x16x32_bf16 v[48:51], v[136:139], v[200:203], v[48:51]
	v_mfma_f32_16x16x32_bf16 v[36:39], v[128:131], v[208:211], v[36:39]
	v_mfma_f32_16x16x32_bf16 v[32:35], v[136:139], v[208:211], v[32:35]
	v_mfma_f32_16x16x32_bf16 v[20:23], v[128:131], v[216:219], v[20:23]
	v_mfma_f32_16x16x32_bf16 v[16:19], v[136:139], v[216:219], v[16:19]
	v_mfma_f32_16x16x32_bf16 v[60:63], v[132:135], v[174:177], v[60:63]
	v_mfma_f32_16x16x32_bf16 v[56:59], v[160:163], v[174:177], v[56:59]
	v_mfma_f32_16x16x32_bf16 v[52:55], v[132:135], v[204:207], v[52:55]
	v_mfma_f32_16x16x32_bf16 v[48:51], v[160:163], v[204:207], v[48:51]
	v_mfma_f32_16x16x32_bf16 v[36:39], v[132:135], v[212:215], v[36:39]
	v_mfma_f32_16x16x32_bf16 v[32:35], v[160:163], v[212:215], v[32:35]
	v_mfma_f32_16x16x32_bf16 v[20:23], v[132:135], v[220:223], v[20:23]
	v_mfma_f32_16x16x32_bf16 v[16:19], v[160:163], v[220:223], v[16:19]
	s_barrier
; #define PG8_STAGE(bufoff, gbase, voff) do { _Pragma("unroll") for (int _i = 0; _i < 2; ++_i) \
;         __builtin_amdgcn_global_load_lds((const unsigned*)((const char*)(gbase) + (voff)[_i]), (LAS unsigned*)(lds + (bufoff) + ldsw + _i * 8192), 16, 0, 0); } while (0)
; #define PG8_WAIT_V(n) asm volatile("s_waitcnt vmcnt(" #n ")" ::: "memory")
; #define PG8_BAR __builtin_amdgcn_s_barrier()
;     __device__ __forceinline__ void operator()(const f32x4 (&acc)[2][2][4][2], const Unit& u, int wr, int wc, int fr, int fq) const {
;         const int row0 = u.pm * BM + wr * 64 + fr, col0 = u.pn * BM + wc * 32 + 4 * fq;
;         if (u.slice >= 0) {
;             float* pb = P + (size_t)u.slice * 512 * DM;
; #pragma unroll
;             for (int ai = 0; ai < 2; ++ai)
; #pragma unroll
;                 for (int m = 0; m < 4; ++m) { const size_t off = (size_t)(row0 - MP + ai * HALF + m * 16) * DM + col0;
; #pragma unroll
;                     for (int bj = 0; bj < 2; ++bj)
; #pragma unroll
;                         for (int n = 0; n < 2; ++n) *(f32x4*)(pb + off + bj * HALF + n * 16) = acc[ai][bj][m][n]; }
;             return;
;         }
;         const float* base = (u.pm < 32) ? base_lo : base_hi;
; #pragma unroll
;         for (int ai = 0; ai < 2; ++ai) {
;             f32x4 bs[4][2][2];
; #pragma unroll
;             for (int m = 0; m < 4; ++m) { const size_t off = (size_t)(row0 + ai * HALF + m * 16) * DM + col0;
; #pragma unroll
;                 for (int bj = 0; bj < 2; ++bj)
; #pragma unroll
;                     for (int n = 0; n < 2; ++n) bs[m][bj][n] = *(const f32x4*)(base + off + bj * HALF + n * 16); }
; #pragma unroll
;             for (int m = 0; m < 4; ++m) { const size_t off = (size_t)(row0 + ai * HALF + m * 16) * DM + col0;
; #pragma unroll
;                 for (int bj = 0; bj < 2; ++bj)
; #pragma unroll
;                     for (int n = 0; n < 2; ++n) *(f32x4*)(out + off + bj * HALF + n * 16) = bs[m][bj][n] + scale * acc[ai][bj][m][n]; }
; template <class Epi, class Sched>
; __device__ __forceinline__ void gemm_phase(LAS unsigned char* lds, const Gemm g, const Sched& S, const Epi& E) {
;     ...
;         for (int t = 0; t < nt; t += 2) {
;     ...
;             PG8_STAGE(PG8_SB(1, 1), b3 + hstep, voffB);
;             PG8_WAIT_V(6); PG8_BAR; PG8_MMA(1, 1, At, B1); PG8_BAR;
	s_add_u32 s16, s22, 0x160080
	s_addc_u32 s17, s23, 0
	s_add_i32 s22, s24, s29
	s_mov_b32 m0, s22
	s_nop 0
	global_load_lds_dwordx4 v148, s[16:17]
	s_add_i32 m0, s22, 0x2000
	s_nop 0
	global_load_lds_dwordx4 v140, s[16:17]
	s_add_u32 s51, s51, 0x100
	s_addc_u32 s52, s52, 0
	s_cmp_ge_i32 s53, s50
	s_mov_b64 s[16:17], s[20:21]
	s_mov_b32 s22, s53
	s_waitcnt vmcnt(6)
	s_barrier
	v_mfma_f32_16x16x32_bf16 v[44:47], v[224:227], v[164:167], v[44:47]
	v_mfma_f32_16x16x32_bf16 v[40:43], v[232:235], v[164:167], v[40:43]
	v_mfma_f32_16x16x32_bf16 v[28:31], v[224:227], v[200:203], v[28:31]
	v_mfma_f32_16x16x32_bf16 v[24:27], v[232:235], v[200:203], v[24:27]
	v_mfma_f32_16x16x32_bf16 v[12:15], v[224:227], v[208:211], v[12:15]
	v_mfma_f32_16x16x32_bf16 v[8:11], v[232:235], v[208:211], v[8:11]
	v_mfma_f32_16x16x32_bf16 v[4:7], v[224:227], v[216:219], v[4:7]
	v_mfma_f32_16x16x32_bf16 v[0:3], v[232:235], v[216:219], v[0:3]
	v_mfma_f32_16x16x32_bf16 v[44:47], v[228:231], v[174:177], v[44:47]
	v_mfma_f32_16x16x32_bf16 v[40:43], v[236:239], v[174:177], v[40:43]
	v_mfma_f32_16x16x32_bf16 v[28:31], v[228:231], v[204:207], v[28:31]
	v_mfma_f32_16x16x32_bf16 v[24:27], v[236:239], v[204:207], v[24:27]
	v_mfma_f32_16x16x32_bf16 v[12:15], v[228:231], v[212:215], v[12:15]
	v_mfma_f32_16x16x32_bf16 v[8:11], v[236:239], v[212:215], v[8:11]
	v_mfma_f32_16x16x32_bf16 v[4:7], v[228:231], v[220:223], v[4:7]
	v_mfma_f32_16x16x32_bf16 v[0:3], v[236:239], v[220:223], v[0:3]
	s_barrier
	s_cbranch_scc0 .LBB0_170
	v_lshl_add_u32 v146, s48, 8, v170
	v_lshl_or_b32 v160, s49, 8, v172
	s_mov_b64 s[16:17], -1
	s_cmp_lt_i32 s82, 0
	v_ashrrev_i32_e32 v161, 31, v160
	v_ashrrev_i32_e32 v147, 31, v146
	s_cbranch_scc0 .LBB0_173
	s_cmp_lt_i32 s48, 32
	s_cselect_b32 s17, s13, s61
	s_cselect_b32 s16, s12, s60
	v_lshlrev_b64 v[162:163], 2, v[160:161]
	v_lshl_add_u64 v[164:165], s[16:17], 0, v[162:163]
	v_lshlrev_b64 v[166:167], 13, v[146:147]
	v_lshl_add_u64 v[128:129], v[164:165], 0, v[166:167]
	global_load_dwordx4 v[174:177], v[128:129], off
	global_load_dwordx4 v[200:203], v[128:129], off offset:64
	global_load_dwordx4 v[204:207], v[128:129], off offset:512
	global_load_dwordx4 v[208:211], v[128:129], off offset:576
	v_or_b32_e32 v128, 16, v146
	v_ashrrev_i32_e32 v129, 31, v128
	v_lshlrev_b64 v[248:249], 13, v[128:129]
	v_lshl_add_u64 v[128:129], v[164:165], 0, v[248:249]
	global_load_dwordx4 v[212:215], v[128:129], off
	global_load_dwordx4 v[216:219], v[128:129], off offset:64
	global_load_dwordx4 v[220:223], v[128:129], off offset:512
	global_load_dwordx4 v[224:227], v[128:129], off offset:576
	v_or_b32_e32 v128, 32, v146
	v_ashrrev_i32_e32 v129, 31, v128
	v_lshlrev_b64 v[188:189], 13, v[128:129]
	v_lshl_add_u64 v[128:129], v[164:165], 0, v[188:189]
	global_load_dwordx4 v[228:231], v[128:129], off
	global_load_dwordx4 v[232:235], v[128:129], off offset:64
	global_load_dwordx4 v[236:239], v[128:129], off offset:512
	global_load_dwordx4 v[240:243], v[128:129], off offset:576
	v_or_b32_e32 v128, 48, v146
	v_ashrrev_i32_e32 v129, 31, v128
	v_lshlrev_b64 v[168:169], 13, v[128:129]
	v_lshl_add_u64 v[128:129], v[164:165], 0, v[168:169]
	global_load_dwordx4 v[244:247], v[128:129], off
	global_load_dwordx4 v[136:139], v[128:129], off offset:64
	global_load_dwordx4 v[132:135], v[128:129], off offset:512
	s_nop 0
	global_load_dwordx4 v[128:131], v[128:129], off offset:576
	v_lshl_add_u64 v[190:191], s[60:61], 0, v[166:167]
	v_lshl_add_u64 v[190:191], v[190:191], 0, v[162:163]
	v_lshl_add_u64 v[188:189], s[60:61], 0, v[188:189]
	v_lshl_add_u64 v[188:189], v[188:189], 0, v[162:163]
	v_lshl_add_u64 v[168:169], s[60:61], 0, v[168:169]
	v_lshl_add_u64 v[168:169], v[168:169], 0, v[162:163]
	s_mov_b64 s[16:17], 0x100000
	s_waitcnt vmcnt(0)
	v_pk_fma_f32 v[176:177], v[126:127], 0.5, v[176:177] op_sel_hi:[1,0,1]
	v_pk_fma_f32 v[174:175], v[124:125], 0.5, v[174:175] op_sel_hi:[1,0,1]
	global_store_dwordx4 v[190:191], v[174:177], off
	v_pk_fma_f32 v[138:139], v[82:83], 0.5, v[138:139] op_sel_hi:[1,0,1]
	s_nop 0
	v_pk_fma_f32 v[176:177], v[122:123], 0.5, v[202:203] op_sel_hi:[1,0,1]
	v_pk_fma_f32 v[174:175], v[120:121], 0.5, v[200:201] op_sel_hi:[1,0,1]
	global_store_dwordx4 v[190:191], v[174:177], off offset:64
	v_pk_fma_f32 v[136:137], v[80:81], 0.5, v[136:137] op_sel_hi:[1,0,1]
	v_pk_fma_f32 v[134:135], v[70:71], 0.5, v[134:135] op_sel_hi:[1,0,1]
	v_pk_fma_f32 v[176:177], v[110:111], 0.5, v[206:207] op_sel_hi:[1,0,1]
	v_pk_fma_f32 v[174:175], v[108:109], 0.5, v[204:205] op_sel_hi:[1,0,1]
	global_store_dwordx4 v[190:191], v[174:177], off offset:512
	v_pk_fma_f32 v[132:133], v[68:69], 0.5, v[132:133] op_sel_hi:[1,0,1]
	v_pk_fma_f32 v[130:131], v[66:67], 0.5, v[130:131] op_sel_hi:[1,0,1]
	v_pk_fma_f32 v[176:177], v[106:107], 0.5, v[210:211] op_sel_hi:[1,0,1]
	v_pk_fma_f32 v[174:175], v[104:105], 0.5, v[208:209] op_sel_hi:[1,0,1]
	global_store_dwordx4 v[190:191], v[174:177], off offset:576
	v_lshl_add_u64 v[190:191], s[60:61], 0, v[248:249]
	v_lshl_add_u64 v[190:191], v[190:191], 0, v[162:163]
	v_pk_fma_f32 v[176:177], v[118:119], 0.5, v[214:215] op_sel_hi:[1,0,1]
	v_pk_fma_f32 v[174:175], v[116:117], 0.5, v[212:213] op_sel_hi:[1,0,1]
	global_store_dwordx4 v[190:191], v[174:177], off
	v_pk_fma_f32 v[128:129], v[64:65], 0.5, v[128:129] op_sel_hi:[1,0,1]
	global_store_dwordx4 v[168:169], v[136:139], off offset:64
	v_pk_fma_f32 v[176:177], v[114:115], 0.5, v[218:219] op_sel_hi:[1,0,1]
	v_pk_fma_f32 v[174:175], v[112:113], 0.5, v[216:217] op_sel_hi:[1,0,1]
	global_store_dwordx4 v[190:191], v[174:177], off offset:64
	global_store_dwordx4 v[168:169], v[132:135], off offset:512
	global_store_dwordx4 v[168:169], v[128:131], off offset:576
;     __device__ __forceinline__ void operator()(const f32x4 (&acc)[2][2][4][2], const Unit& u, int wr, int wc, int fr, int fq) const {
;     ...
;         for (int ai = 0; ai < 2; ++ai) {
;             f32x4 bs[4][2][2];
; #pragma unroll
;             for (int m = 0; m < 4; ++m) { const size_t off = (size_t)(row0 + ai * HALF + m * 16) * DM + col0;
; #pragma unroll
;                 for (int bj = 0; bj < 2; ++bj)
; #pragma unroll
;                     for (int n = 0; n < 2; ++n) bs[m][bj][n] = *(const f32x4*)(base + off + bj * HALF + n * 16); }
; #pragma unroll
;             for (int m = 0; m < 4; ++m) { const size_t off = (size_t)(row0 + ai * HALF + m * 16) * DM + col0;
; #pragma unroll
;                 for (int bj = 0; bj < 2; ++bj)
; #pragma unroll
;                     for (int n = 0; n < 2; ++n) *(f32x4*)(out + off + bj * HALF + n * 16) = bs[m][bj][n] + scale * acc[ai][bj][m][n]; }
	v_pk_fma_f32 v[176:177], v[94:95], 0.5, v[222:223] op_sel_hi:[1,0,1]
	v_pk_fma_f32 v[174:175], v[92:93], 0.5, v[220:221] op_sel_hi:[1,0,1]
	global_store_dwordx4 v[190:191], v[174:177], off offset:512
	s_nop 1
	v_pk_fma_f32 v[176:177], v[90:91], 0.5, v[226:227] op_sel_hi:[1,0,1]
	v_pk_fma_f32 v[174:175], v[88:89], 0.5, v[224:225] op_sel_hi:[1,0,1]
	global_store_dwordx4 v[190:191], v[174:177], off offset:576
	s_nop 1
	v_pk_fma_f32 v[176:177], v[102:103], 0.5, v[230:231] op_sel_hi:[1,0,1]
	v_pk_fma_f32 v[174:175], v[100:101], 0.5, v[228:229] op_sel_hi:[1,0,1]
	global_store_dwordx4 v[188:189], v[174:177], off
	s_nop 1
	v_pk_fma_f32 v[176:177], v[98:99], 0.5, v[234:235] op_sel_hi:[1,0,1]
	v_pk_fma_f32 v[174:175], v[96:97], 0.5, v[232:233] op_sel_hi:[1,0,1]
	global_store_dwordx4 v[188:189], v[174:177], off offset:64
	s_nop 1
	v_pk_fma_f32 v[176:177], v[78:79], 0.5, v[238:239] op_sel_hi:[1,0,1]
	v_pk_fma_f32 v[174:175], v[76:77], 0.5, v[236:237] op_sel_hi:[1,0,1]
	global_store_dwordx4 v[188:189], v[174:177], off offset:512
	s_nop 1
	v_pk_fma_f32 v[176:177], v[74:75], 0.5, v[242:243] op_sel_hi:[1,0,1]
	v_pk_fma_f32 v[174:175], v[72:73], 0.5, v[240:241] op_sel_hi:[1,0,1]
	global_store_dwordx4 v[188:189], v[174:177], off offset:576
	s_nop 1
	v_pk_fma_f32 v[176:177], v[86:87], 0.5, v[246:247] op_sel_hi:[1,0,1]
	v_pk_fma_f32 v[174:175], v[84:85], 0.5, v[244:245] op_sel_hi:[1,0,1]
	global_store_dwordx4 v[168:169], v[174:177], off
	v_lshl_add_u64 v[168:169], v[166:167], 0, s[16:17]
	v_lshl_add_u64 v[128:129], v[164:165], 0, v[168:169]
	global_load_dwordx4 v[174:177], v[128:129], off
	global_load_dwordx4 v[200:203], v[128:129], off offset:64
	global_load_dwordx4 v[204:207], v[128:129], off offset:512
	global_load_dwordx4 v[208:211], v[128:129], off offset:576
	s_mov_b64 s[16:17], 0x120000
	v_lshl_add_u64 v[188:189], v[166:167], 0, s[16:17]
	v_lshl_add_u64 v[128:129], v[164:165], 0, v[188:189]
	global_load_dwordx4 v[212:215], v[128:129], off
	global_load_dwordx4 v[216:219], v[128:129], off offset:64
	global_load_dwordx4 v[220:223], v[128:129], off offset:512
	global_load_dwordx4 v[224:227], v[128:129], off offset:576
	s_mov_b64 s[16:17], 0x140000
	v_lshl_add_u64 v[190:191], v[166:167], 0, s[16:17]
	v_lshl_add_u64 v[128:129], v[164:165], 0, v[190:191]
	s_mov_b64 s[16:17], 0x160000
	global_load_dwordx4 v[228:231], v[128:129], off
	global_load_dwordx4 v[232:235], v[128:129], off offset:64
	global_load_dwordx4 v[236:239], v[128:129], off offset:512
	global_load_dwordx4 v[240:243], v[128:129], off offset:576
	v_lshl_add_u64 v[166:167], v[166:167], 0, s[16:17]
	v_lshl_add_u64 v[128:129], v[164:165], 0, v[166:167]
	global_load_dwordx4 v[244:247], v[128:129], off
	global_load_dwordx4 v[136:139], v[128:129], off offset:64
	global_load_dwordx4 v[132:135], v[128:129], off offset:512
	s_nop 0
	global_load_dwordx4 v[128:131], v[128:129], off offset:576
	v_lshl_add_u64 v[164:165], s[60:61], 0, v[168:169]
	v_lshl_add_u64 v[164:165], v[164:165], 0, v[162:163]
	s_mov_b64 s[16:17], 0
	s_waitcnt vmcnt(0)
	v_pk_fma_f32 v[176:177], v[62:63], 0.5, v[176:177] op_sel_hi:[1,0,1]
	v_pk_fma_f32 v[174:175], v[60:61], 0.5, v[174:175] op_sel_hi:[1,0,1]
	global_store_dwordx4 v[164:165], v[174:177], off
	v_pk_fma_f32 v[138:139], v[18:19], 0.5, v[138:139] op_sel_hi:[1,0,1]
	s_nop 0
	v_pk_fma_f32 v[176:177], v[58:59], 0.5, v[202:203] op_sel_hi:[1,0,1]
	v_pk_fma_f32 v[174:175], v[56:57], 0.5, v[200:201] op_sel_hi:[1,0,1]
	global_store_dwordx4 v[164:165], v[174:177], off offset:64
	v_pk_fma_f32 v[136:137], v[16:17], 0.5, v[136:137] op_sel_hi:[1,0,1]
	v_pk_fma_f32 v[134:135], v[6:7], 0.5, v[134:135] op_sel_hi:[1,0,1]
	v_pk_fma_f32 v[176:177], v[46:47], 0.5, v[206:207] op_sel_hi:[1,0,1]
	v_pk_fma_f32 v[174:175], v[44:45], 0.5, v[204:205] op_sel_hi:[1,0,1]
	global_store_dwordx4 v[164:165], v[174:177], off offset:512
	v_pk_fma_f32 v[132:133], v[4:5], 0.5, v[132:133] op_sel_hi:[1,0,1]
	v_pk_fma_f32 v[130:131], v[2:3], 0.5, v[130:131] op_sel_hi:[1,0,1]
	v_pk_fma_f32 v[176:177], v[42:43], 0.5, v[210:211] op_sel_hi:[1,0,1]
	v_pk_fma_f32 v[174:175], v[40:41], 0.5, v[208:209] op_sel_hi:[1,0,1]
	global_store_dwordx4 v[164:165], v[174:177], off offset:576
	v_lshl_add_u64 v[164:165], s[60:61], 0, v[188:189]
	v_lshl_add_u64 v[164:165], v[164:165], 0, v[162:163]
	v_pk_fma_f32 v[176:177], v[54:55], 0.5, v[214:215] op_sel_hi:[1,0,1]
	v_pk_fma_f32 v[174:175], v[52:53], 0.5, v[212:213] op_sel_hi:[1,0,1]
	global_store_dwordx4 v[164:165], v[174:177], off
	v_pk_fma_f32 v[128:129], v[0:1], 0.5, v[128:129] op_sel_hi:[1,0,1]
	s_nop 0
	v_pk_fma_f32 v[176:177], v[50:51], 0.5, v[218:219] op_sel_hi:[1,0,1]
	v_pk_fma_f32 v[174:175], v[48:49], 0.5, v[216:217] op_sel_hi:[1,0,1]
	global_store_dwordx4 v[164:165], v[174:177], off offset:64
	s_nop 1
	v_pk_fma_f32 v[176:177], v[30:31], 0.5, v[222:223] op_sel_hi:[1,0,1]
	v_pk_fma_f32 v[174:175], v[28:29], 0.5, v[220:221] op_sel_hi:[1,0,1]
	global_store_dwordx4 v[164:165], v[174:177], off offset:512
	s_nop 1
	v_pk_fma_f32 v[176:177], v[26:27], 0.5, v[226:227] op_sel_hi:[1,0,1]
	v_pk_fma_f32 v[174:175], v[24:25], 0.5, v[224:225] op_sel_hi:[1,0,1]
	global_store_dwordx4 v[164:165], v[174:177], off offset:576
	v_lshl_add_u64 v[164:165], s[60:61], 0, v[190:191]
	v_lshl_add_u64 v[164:165], v[164:165], 0, v[162:163]
	v_pk_fma_f32 v[176:177], v[38:39], 0.5, v[230:231] op_sel_hi:[1,0,1]
	v_pk_fma_f32 v[174:175], v[36:37], 0.5, v[228:229] op_sel_hi:[1,0,1]
	global_store_dwordx4 v[164:165], v[174:177], off
	s_nop 1
	v_pk_fma_f32 v[176:177], v[34:35], 0.5, v[234:235] op_sel_hi:[1,0,1]
	v_pk_fma_f32 v[174:175], v[32:33], 0.5, v[232:233] op_sel_hi:[1,0,1]
	global_store_dwordx4 v[164:165], v[174:177], off offset:64
	s_nop 1
	v_pk_fma_f32 v[176:177], v[14:15], 0.5, v[238:239] op_sel_hi:[1,0,1]
	v_pk_fma_f32 v[174:175], v[12:13], 0.5, v[236:237] op_sel_hi:[1,0,1]
	global_store_dwordx4 v[164:165], v[174:177], off offset:512
	s_nop 1
	v_pk_fma_f32 v[176:177], v[10:11], 0.5, v[242:243] op_sel_hi:[1,0,1]
	v_pk_fma_f32 v[174:175], v[8:9], 0.5, v[240:241] op_sel_hi:[1,0,1]
	global_store_dwordx4 v[164:165], v[174:177], off offset:576
	v_lshl_add_u64 v[164:165], s[60:61], 0, v[166:167]
	v_lshl_add_u64 v[162:163], v[164:165], 0, v[162:163]
	v_pk_fma_f32 v[176:177], v[22:23], 0.5, v[246:247] op_sel_hi:[1,0,1]
	v_pk_fma_f32 v[174:175], v[20:21], 0.5, v[244:245] op_sel_hi:[1,0,1]
	global_store_dwordx4 v[162:163], v[174:177], off
	global_store_dwordx4 v[162:163], v[136:139], off offset:64
	global_store_dwordx4 v[162:163], v[132:135], off offset:512
	global_store_dwordx4 v[162:163], v[128:131], off offset:576

; #define PG8_STAGE(bufoff, gbase, voff) do { _Pragma("unroll") for (int _i = 0; _i < 2; ++_i) \
;         __builtin_amdgcn_global_load_lds((const unsigned*)((const char*)(gbase) + (voff)[_i]), (LAS unsigned*)(lds + (bufoff) + ldsw + _i * 8192), 16, 0, 0); } while (0)
; #define PG8_LDA(dst, b, h) do { _Pragma("unroll") for (int m = 0; m < 4; ++m) _Pragma("unroll") for (int k = 0; k < 2; ++k) dst[m][k] = *(const LAS bf16x8*)(lds + PG8_SA(b, h) + aoff + m * 2048 + k * 1024); } while (0)
; #define PG8_LDB(dst, b, h) do { _Pragma("unroll") for (int n = 0; n < 2; ++n) _Pragma("unroll") for (int k = 0; k < 2; ++k) dst[n][k] = *(const LAS bf16x8*)(lds + PG8_SB(b, h) + boff + n * 2048 + k * 1024); } while (0)
; #define PG8_MMA(ai, bj, At, Bt) do { __builtin_amdgcn_s_setprio(1); _Pragma("unroll") for (int m = 0; m < 4; ++m) _Pragma("unroll") for (int n = 0; n < 2; ++n) _Pragma("unroll") for (int k = 0; k < 2; ++k) \
;         acc[ai][bj][m][n] = __builtin_amdgcn_mfma_f32_16x16x32_bf16(Bt[n][k], At[m][k], acc[ai][bj][m][n], 0, 0, 0); __builtin_amdgcn_s_setprio(0); } while (0)
; #define PG8_WAIT_V(n) asm volatile("s_waitcnt vmcnt(" #n ")" ::: "memory")
; #define PG8_WAIT_L(n) asm volatile("s_waitcnt lgkmcnt(" #n ")" ::: "memory")
; template <class Epi, class Sched>
; __device__ __forceinline__ void gemm_phase(LAS unsigned char* lds, const Gemm g, const Sched& S, const Epi& E) {
;     ...
;         for (int t = 0; t < nt; t += 2) {
;             const bool last = (t == nt - 2);
;             const char* a1 = cA + (size_t)(t + 1) * kstep;
;             const char* a2 = last ? nA : cA + (size_t)(t + 2) * kstep; const char* b2 = last ? nB : cB + (size_t)(t + 2) * kstep;
;             const char* a3 = a2 + kstep; const char* b3 = b2 + kstep;
;             PG8_LDB(B0, 0, 0); PG8_SCHED; PG8_LDA(At, 0, 0); PG8_STAGE(PG8_SA(1, 1), a1 + hstep, voffA);
;             PG8_WAIT_L(8); PG8_BAR; PG8_WAIT_L(0); PG8_MMA(0, 0, At, B0); PG8_BAR; PG8_SCHED;
;             PG8_LDB(B1, 0, 1); PG8_STAGE(PG8_SB(0, 0), b2, voffB);
;             PG8_BAR; PG8_WAIT_L(0); PG8_MMA(0, 1, At, B1); PG8_BAR;
;             PG8_LDA(At, 0, 1); PG8_STAGE(PG8_SA(0, 0), a2, voffA);
;             PG8_BAR; PG8_WAIT_L(0); PG8_MMA(1, 0, At, B0); PG8_BAR; PG8_SCHED;
;             PG8_STAGE(PG8_SB(0, 1), b2 + hstep, voffB);
;             PG8_WAIT_V(6); PG8_BAR; PG8_MMA(1, 1, At, B1); PG8_BAR;
.LBB0_267:
	s_add_i32 s47, s22, 2
	s_add_u32 s20, s16, 0x100
	s_addc_u32 s21, s17, 0
	s_add_i32 s48, 0, 0x10000
	ds_read_b128 v[128:131], v161
	ds_read_b128 v[132:135], v161 offset:1024
	ds_read_b128 v[136:139], v161 offset:2048
	ds_read_b128 v[140:143], v161 offset:3072
	s_cmp_eq_u32 s11, s22
	s_cselect_b32 s22, s4, s13
	s_cselect_b32 s25, s7, s21
	s_cselect_b32 s24, s6, s20
	s_cselect_b32 s23, s5, s15
	s_add_i32 m0, s33, 0xc000
	ds_read_b128 v[144:147], v203
	ds_read_b128 v[166:169], v203 offset:1024
	ds_read_b128 v[170:173], v203 offset:2048
	ds_read_b128 v[174:177], v203 offset:3072
	ds_read_b128 v[204:207], v203 offset:4096
	ds_read_b128 v[208:211], v203 offset:5120
	ds_read_b128 v[212:215], v203 offset:6144
	ds_read_b128 v[216:219], v203 offset:7168
	global_load_lds_dwordx4 v162, s[16:17]
	s_add_i32 m0, s33, 0xe000
	s_nop 0
	global_load_lds_dwordx4 v164, s[16:17]
	s_waitcnt lgkmcnt(8)
	s_barrier
	s_waitcnt lgkmcnt(0)
	v_mfma_f32_16x16x32_bf16 v[124:127], v[128:131], v[144:147], v[124:127]
	v_mfma_f32_16x16x32_bf16 v[120:123], v[136:139], v[144:147], v[120:123]
	v_mfma_f32_16x16x32_bf16 v[116:119], v[128:131], v[170:173], v[116:119]
	v_mfma_f32_16x16x32_bf16 v[112:115], v[136:139], v[170:173], v[112:115]
	v_mfma_f32_16x16x32_bf16 v[100:103], v[128:131], v[204:207], v[100:103]
	v_mfma_f32_16x16x32_bf16 v[96:99], v[136:139], v[204:207], v[96:99]
	v_mfma_f32_16x16x32_bf16 v[84:87], v[128:131], v[212:215], v[84:87]
	v_mfma_f32_16x16x32_bf16 v[80:83], v[136:139], v[212:215], v[80:83]
	v_mfma_f32_16x16x32_bf16 v[124:127], v[132:135], v[166:169], v[124:127]
	v_mfma_f32_16x16x32_bf16 v[120:123], v[140:143], v[166:169], v[120:123]
	v_mfma_f32_16x16x32_bf16 v[116:119], v[132:135], v[174:177], v[116:119]
	v_mfma_f32_16x16x32_bf16 v[112:115], v[140:143], v[174:177], v[112:115]
	v_mfma_f32_16x16x32_bf16 v[100:103], v[132:135], v[208:211], v[100:103]
	v_mfma_f32_16x16x32_bf16 v[96:99], v[140:143], v[208:211], v[96:99]
	v_mfma_f32_16x16x32_bf16 v[84:87], v[132:135], v[216:219], v[84:87]
	v_mfma_f32_16x16x32_bf16 v[80:83], v[140:143], v[216:219], v[80:83]
	s_barrier
	s_add_i32 s49, 0, 0x14000
	s_add_i32 s16, s48, s31
	ds_read_b128 v[220:223], v161 offset:16384
	ds_read_b128 v[224:227], v161 offset:17408
	ds_read_b128 v[228:231], v161 offset:18432
	ds_read_b128 v[232:235], v161 offset:19456
	s_add_u32 s84, s22, 0x80
	s_addc_u32 s85, s23, 0
	s_mov_b32 m0, s16
	s_nop 0
	global_load_lds_dwordx4 v148, s[22:23]
	s_add_i32 m0, s16, 0x2000
	s_nop 0
	global_load_lds_dwordx4 v160, s[22:23]
	s_barrier
	s_waitcnt lgkmcnt(0)
	v_mfma_f32_16x16x32_bf16 v[108:111], v[220:223], v[144:147], v[108:111]
	v_mfma_f32_16x16x32_bf16 v[104:107], v[228:231], v[144:147], v[104:107]
	v_mfma_f32_16x16x32_bf16 v[92:95], v[220:223], v[170:173], v[92:95]
	v_mfma_f32_16x16x32_bf16 v[88:91], v[228:231], v[170:173], v[88:91]
	v_mfma_f32_16x16x32_bf16 v[76:79], v[220:223], v[204:207], v[76:79]
	v_mfma_f32_16x16x32_bf16 v[72:75], v[228:231], v[204:207], v[72:75]
	v_mfma_f32_16x16x32_bf16 v[68:71], v[220:223], v[212:215], v[68:71]
	v_mfma_f32_16x16x32_bf16 v[64:67], v[228:231], v[212:215], v[64:67]
	v_mfma_f32_16x16x32_bf16 v[108:111], v[224:227], v[166:169], v[108:111]
	v_mfma_f32_16x16x32_bf16 v[104:107], v[232:235], v[166:169], v[104:107]
	v_mfma_f32_16x16x32_bf16 v[92:95], v[224:227], v[174:177], v[92:95]
	v_mfma_f32_16x16x32_bf16 v[88:91], v[232:235], v[174:177], v[88:91]
	v_mfma_f32_16x16x32_bf16 v[76:79], v[224:227], v[208:211], v[76:79]
	v_mfma_f32_16x16x32_bf16 v[72:75], v[232:235], v[208:211], v[72:75]
	v_mfma_f32_16x16x32_bf16 v[68:71], v[224:227], v[216:219], v[68:71]
	v_mfma_f32_16x16x32_bf16 v[64:67], v[232:235], v[216:219], v[64:67]
	s_barrier
	s_mov_b32 m0, s33
	s_add_u32 s86, s24, 0x80
	s_addc_u32 s87, s25, 0
	ds_read_b128 v[144:147], v203 offset:16384
	ds_read_b128 v[166:169], v203 offset:17408
	ds_read_b128 v[170:173], v203 offset:18432
	ds_read_b128 v[174:177], v203 offset:19456
	ds_read_b128 v[204:207], v203 offset:20480
	ds_read_b128 v[208:211], v203 offset:21504
	ds_read_b128 v[212:215], v203 offset:22528
	ds_read_b128 v[216:219], v203 offset:23552
	global_load_lds_dwordx4 v148, s[24:25]
	s_mov_b32 m0, s34
	s_nop 0
	global_load_lds_dwordx4 v160, s[24:25]
	s_barrier
	s_waitcnt lgkmcnt(0)
	v_mfma_f32_16x16x32_bf16 v[60:63], v[128:131], v[144:147], v[60:63]
	v_mfma_f32_16x16x32_bf16 v[56:59], v[136:139], v[144:147], v[56:59]
	v_mfma_f32_16x16x32_bf16 v[52:55], v[128:131], v[170:173], v[52:55]
	v_mfma_f32_16x16x32_bf16 v[48:51], v[136:139], v[170:173], v[48:51]
	v_mfma_f32_16x16x32_bf16 v[36:39], v[128:131], v[204:207], v[36:39]
	v_mfma_f32_16x16x32_bf16 v[32:35], v[136:139], v[204:207], v[32:35]
	v_mfma_f32_16x16x32_bf16 v[20:23], v[128:131], v[212:215], v[20:23]
	v_mfma_f32_16x16x32_bf16 v[16:19], v[136:139], v[212:215], v[16:19]
	v_mfma_f32_16x16x32_bf16 v[60:63], v[132:135], v[166:169], v[60:63]
	v_mfma_f32_16x16x32_bf16 v[56:59], v[140:143], v[166:169], v[56:59]
	v_mfma_f32_16x16x32_bf16 v[52:55], v[132:135], v[174:177], v[52:55]
	v_mfma_f32_16x16x32_bf16 v[48:51], v[140:143], v[174:177], v[48:51]
	v_mfma_f32_16x16x32_bf16 v[36:39], v[132:135], v[208:211], v[36:39]
	v_mfma_f32_16x16x32_bf16 v[32:35], v[140:143], v[208:211], v[32:35]
	v_mfma_f32_16x16x32_bf16 v[20:23], v[132:135], v[216:219], v[20:23]
	v_mfma_f32_16x16x32_bf16 v[16:19], v[140:143], v[216:219], v[16:19]
	s_barrier
	s_add_u32 s16, s22, 0x80000
	s_addc_u32 s17, s23, 0
	s_add_i32 s48, s49, s31
	s_mov_b32 m0, s48
	s_nop 0
	global_load_lds_dwordx4 v148, s[16:17]
	s_add_i32 m0, s48, 0x2000
	s_nop 0
	global_load_lds_dwordx4 v160, s[16:17]
	s_waitcnt vmcnt(6)
	s_barrier
; #define PG8_STAGE(bufoff, gbase, voff) do { _Pragma("unroll") for (int _i = 0; _i < 2; ++_i) \
;         __builtin_amdgcn_global_load_lds((const unsigned*)((const char*)(gbase) + (voff)[_i]), (LAS unsigned*)(lds + (bufoff) + ldsw + _i * 8192), 16, 0, 0); } while (0)
; #define PG8_LDA(dst, b, h) do { _Pragma("unroll") for (int m = 0; m < 4; ++m) _Pragma("unroll") for (int k = 0; k < 2; ++k) dst[m][k] = *(const LAS bf16x8*)(lds + PG8_SA(b, h) + aoff + m * 2048 + k * 1024); } while (0)
; #define PG8_LDB(dst, b, h) do { _Pragma("unroll") for (int n = 0; n < 2; ++n) _Pragma("unroll") for (int k = 0; k < 2; ++k) dst[n][k] = *(const LAS bf16x8*)(lds + PG8_SB(b, h) + boff + n * 2048 + k * 1024); } while (0)
; #define PG8_MMA(ai, bj, At, Bt) do { __builtin_amdgcn_s_setprio(1); _Pragma("unroll") for (int m = 0; m < 4; ++m) _Pragma("unroll") for (int n = 0; n < 2; ++n) _Pragma("unroll") for (int k = 0; k < 2; ++k) \
;         acc[ai][bj][m][n] = __builtin_amdgcn_mfma_f32_16x16x32_bf16(Bt[n][k], At[m][k], acc[ai][bj][m][n], 0, 0, 0); __builtin_amdgcn_s_setprio(0); } while (0)
; #define PG8_WAIT_V(n) asm volatile("s_waitcnt vmcnt(" #n ")" ::: "memory")
; #define PG8_WAIT_L(n) asm volatile("s_waitcnt lgkmcnt(" #n ")" ::: "memory")
; #define PG8_BAR __builtin_amdgcn_s_barrier()
; #define PG8_SCHED __builtin_amdgcn_sched_barrier(0)
; template <class Epi, class Sched>
; __device__ __forceinline__ void gemm_phase(LAS unsigned char* lds, const Gemm g, const Sched& S, const Epi& E) {
;     ...
;             PG8_WAIT_V(6); PG8_BAR; PG8_MMA(1, 1, At, B1); PG8_BAR;
;             PG8_LDB(B0, 1, 0); PG8_SCHED; PG8_LDA(At, 1, 0); PG8_STAGE(PG8_SA(0, 1), a2 + hstep, voffA);
;             PG8_WAIT_L(8); PG8_BAR; PG8_WAIT_L(0); PG8_MMA(0, 0, At, B0); PG8_BAR; PG8_SCHED;
;             PG8_LDB(B1, 1, 1); PG8_STAGE(PG8_SB(1, 0), b3, voffB);
;             PG8_BAR; PG8_WAIT_L(0); PG8_MMA(0, 1, At, B1); PG8_BAR;
;             PG8_LDA(At, 1, 1); PG8_STAGE(PG8_SA(1, 0), a3, voffA);
;             PG8_BAR; PG8_WAIT_L(0); PG8_MMA(1, 0, At, B0); PG8_BAR; PG8_SCHED;
	v_mfma_f32_16x16x32_bf16 v[44:47], v[220:223], v[144:147], v[44:47]
	v_mfma_f32_16x16x32_bf16 v[40:43], v[228:231], v[144:147], v[40:43]
	v_mfma_f32_16x16x32_bf16 v[28:31], v[220:223], v[170:173], v[28:31]
	v_mfma_f32_16x16x32_bf16 v[24:27], v[228:231], v[170:173], v[24:27]
	v_mfma_f32_16x16x32_bf16 v[12:15], v[220:223], v[204:207], v[12:15]
	v_mfma_f32_16x16x32_bf16 v[8:11], v[228:231], v[204:207], v[8:11]
	v_mfma_f32_16x16x32_bf16 v[4:7], v[220:223], v[212:215], v[4:7]
	v_mfma_f32_16x16x32_bf16 v[0:3], v[228:231], v[212:215], v[0:3]
	v_mfma_f32_16x16x32_bf16 v[44:47], v[224:227], v[166:169], v[44:47]
	v_mfma_f32_16x16x32_bf16 v[40:43], v[232:235], v[166:169], v[40:43]
	v_mfma_f32_16x16x32_bf16 v[28:31], v[224:227], v[174:177], v[28:31]
	v_mfma_f32_16x16x32_bf16 v[24:27], v[232:235], v[174:177], v[24:27]
	v_mfma_f32_16x16x32_bf16 v[12:15], v[224:227], v[208:211], v[12:15]
	v_mfma_f32_16x16x32_bf16 v[8:11], v[232:235], v[208:211], v[8:11]
	v_mfma_f32_16x16x32_bf16 v[4:7], v[224:227], v[216:219], v[4:7]
	v_mfma_f32_16x16x32_bf16 v[0:3], v[232:235], v[216:219], v[0:3]
	s_barrier
	s_add_i32 s48, 0, 0x18000
	ds_read_b128 v[128:131], v161 offset:32768
	ds_read_b128 v[132:135], v161 offset:33792
	ds_read_b128 v[136:139], v161 offset:34816
	ds_read_b128 v[140:143], v161 offset:35840
	s_add_u32 s16, s24, 0x80000
	s_addc_u32 s17, s25, 0
	s_mov_b32 m0, s35
	ds_read_b128 v[144:147], v203 offset:32768
	ds_read_b128 v[166:169], v203 offset:33792
	ds_read_b128 v[170:173], v203 offset:34816
	ds_read_b128 v[174:177], v203 offset:35840
	ds_read_b128 v[204:207], v203 offset:36864
	ds_read_b128 v[208:211], v203 offset:37888
	ds_read_b128 v[212:215], v203 offset:38912
	ds_read_b128 v[216:219], v203 offset:39936
	global_load_lds_dwordx4 v148, s[16:17]
	s_mov_b32 m0, s36
	s_nop 0
	global_load_lds_dwordx4 v160, s[16:17]
	s_waitcnt lgkmcnt(8)
	s_barrier
	s_waitcnt lgkmcnt(0)
	v_mfma_f32_16x16x32_bf16 v[124:127], v[128:131], v[144:147], v[124:127]
	v_mfma_f32_16x16x32_bf16 v[120:123], v[136:139], v[144:147], v[120:123]
	v_mfma_f32_16x16x32_bf16 v[116:119], v[128:131], v[170:173], v[116:119]
	v_mfma_f32_16x16x32_bf16 v[112:115], v[136:139], v[170:173], v[112:115]
	v_mfma_f32_16x16x32_bf16 v[100:103], v[128:131], v[204:207], v[100:103]
	v_mfma_f32_16x16x32_bf16 v[96:99], v[136:139], v[204:207], v[96:99]
	v_mfma_f32_16x16x32_bf16 v[84:87], v[128:131], v[212:215], v[84:87]
	v_mfma_f32_16x16x32_bf16 v[80:83], v[136:139], v[212:215], v[80:83]
	v_mfma_f32_16x16x32_bf16 v[124:127], v[132:135], v[166:169], v[124:127]
	v_mfma_f32_16x16x32_bf16 v[120:123], v[140:143], v[166:169], v[120:123]
	v_mfma_f32_16x16x32_bf16 v[116:119], v[132:135], v[174:177], v[116:119]
	v_mfma_f32_16x16x32_bf16 v[112:115], v[140:143], v[174:177], v[112:115]
	v_mfma_f32_16x16x32_bf16 v[100:103], v[132:135], v[208:211], v[100:103]
	v_mfma_f32_16x16x32_bf16 v[96:99], v[140:143], v[208:211], v[96:99]
	v_mfma_f32_16x16x32_bf16 v[84:87], v[132:135], v[216:219], v[84:87]
	v_mfma_f32_16x16x32_bf16 v[80:83], v[140:143], v[216:219], v[80:83]
	s_barrier
	s_add_i32 s24, 0, 0x1c000
	s_add_i32 s16, s48, s31
	s_mov_b32 m0, s16
	ds_read_b128 v[220:223], v161 offset:49152
	ds_read_b128 v[224:227], v161 offset:50176
	ds_read_b128 v[228:231], v161 offset:51200
	ds_read_b128 v[232:235], v161 offset:52224
	global_load_lds_dwordx4 v148, s[84:85]
	s_add_i32 m0, s16, 0x2000
	s_nop 0
	global_load_lds_dwordx4 v160, s[84:85]
	s_barrier
	s_waitcnt lgkmcnt(0)
	v_mfma_f32_16x16x32_bf16 v[108:111], v[220:223], v[144:147], v[108:111]
	v_mfma_f32_16x16x32_bf16 v[104:107], v[228:231], v[144:147], v[104:107]
	v_mfma_f32_16x16x32_bf16 v[92:95], v[220:223], v[170:173], v[92:95]
	v_mfma_f32_16x16x32_bf16 v[88:91], v[228:231], v[170:173], v[88:91]
	v_mfma_f32_16x16x32_bf16 v[76:79], v[220:223], v[204:207], v[76:79]
	v_mfma_f32_16x16x32_bf16 v[72:75], v[228:231], v[204:207], v[72:75]
	v_mfma_f32_16x16x32_bf16 v[68:71], v[220:223], v[212:215], v[68:71]
	v_mfma_f32_16x16x32_bf16 v[64:67], v[228:231], v[212:215], v[64:67]
	v_mfma_f32_16x16x32_bf16 v[108:111], v[224:227], v[166:169], v[108:111]
	v_mfma_f32_16x16x32_bf16 v[104:107], v[232:235], v[166:169], v[104:107]
	v_mfma_f32_16x16x32_bf16 v[92:95], v[224:227], v[174:177], v[92:95]
	v_mfma_f32_16x16x32_bf16 v[88:91], v[232:235], v[174:177], v[88:91]
	v_mfma_f32_16x16x32_bf16 v[76:79], v[224:227], v[208:211], v[76:79]
	v_mfma_f32_16x16x32_bf16 v[72:75], v[232:235], v[208:211], v[72:75]
	v_mfma_f32_16x16x32_bf16 v[68:71], v[224:227], v[216:219], v[68:71]
	v_mfma_f32_16x16x32_bf16 v[64:67], v[232:235], v[216:219], v[64:67]
	s_barrier
	s_mov_b32 m0, s39
	ds_read_b128 v[144:147], v203 offset:49152
	ds_read_b128 v[166:169], v203 offset:50176
	ds_read_b128 v[170:173], v203 offset:51200
	ds_read_b128 v[174:177], v203 offset:52224
	ds_read_b128 v[204:207], v203 offset:53248
	ds_read_b128 v[208:211], v203 offset:54272
	ds_read_b128 v[212:215], v203 offset:55296
	ds_read_b128 v[216:219], v203 offset:56320
	global_load_lds_dwordx4 v148, s[86:87]
	s_mov_b32 m0, s40
	s_nop 0
	global_load_lds_dwordx4 v160, s[86:87]
	s_barrier
	s_waitcnt lgkmcnt(0)
	v_mfma_f32_16x16x32_bf16 v[60:63], v[128:131], v[144:147], v[60:63]
	v_mfma_f32_16x16x32_bf16 v[56:59], v[136:139], v[144:147], v[56:59]
	v_mfma_f32_16x16x32_bf16 v[52:55], v[128:131], v[170:173], v[52:55]
	v_mfma_f32_16x16x32_bf16 v[48:51], v[136:139], v[170:173], v[48:51]
	v_mfma_f32_16x16x32_bf16 v[36:39], v[128:131], v[204:207], v[36:39]
	v_mfma_f32_16x16x32_bf16 v[32:35], v[136:139], v[204:207], v[32:35]
	v_mfma_f32_16x16x32_bf16 v[20:23], v[128:131], v[212:215], v[20:23]
	v_mfma_f32_16x16x32_bf16 v[16:19], v[136:139], v[212:215], v[16:19]
	v_mfma_f32_16x16x32_bf16 v[60:63], v[132:135], v[166:169], v[60:63]
	v_mfma_f32_16x16x32_bf16 v[56:59], v[140:143], v[166:169], v[56:59]
	v_mfma_f32_16x16x32_bf16 v[52:55], v[132:135], v[174:177], v[52:55]
	v_mfma_f32_16x16x32_bf16 v[48:51], v[140:143], v[174:177], v[48:51]
	v_mfma_f32_16x16x32_bf16 v[36:39], v[132:135], v[208:211], v[36:39]
	v_mfma_f32_16x16x32_bf16 v[32:35], v[140:143], v[208:211], v[32:35]
	v_mfma_f32_16x16x32_bf16 v[20:23], v[132:135], v[216:219], v[20:23]
	v_mfma_f32_16x16x32_bf16 v[16:19], v[140:143], v[216:219], v[16:19]
	s_barrier
; #define PG8_STAGE(bufoff, gbase, voff) do { _Pragma("unroll") for (int _i = 0; _i < 2; ++_i) \
;         __builtin_amdgcn_global_load_lds((const unsigned*)((const char*)(gbase) + (voff)[_i]), (LAS unsigned*)(lds + (bufoff) + ldsw + _i * 8192), 16, 0, 0); } while (0)
; #define PG8_WAIT_V(n) asm volatile("s_waitcnt vmcnt(" #n ")" ::: "memory")
; #define PG8_BAR __builtin_amdgcn_s_barrier()
;     __device__ __forceinline__ void operator()(const f32x4 (&acc)[2][2][4][2], const Unit& u, int wr, int wc, int fr, int fq) const {
;         const int row0 = u.pm * BM + wr * 64 + fr, col0 = u.pn * BM + wc * 32 + 4 * fq;
;         if (u.slice >= 0) {
;             float* pb = P + (size_t)u.slice * 512 * DM;
; #pragma unroll
;             for (int ai = 0; ai < 2; ++ai)
; #pragma unroll
;                 for (int m = 0; m < 4; ++m) { const size_t off = (size_t)(row0 - MP + ai * HALF + m * 16) * DM + col0;
; #pragma unroll
;                     for (int bj = 0; bj < 2; ++bj)
; #pragma unroll
;                         for (int n = 0; n < 2; ++n) *(f32x4*)(pb + off + bj * HALF + n * 16) = acc[ai][bj][m][n]; }
;             return;
;         }
;         const float* base = (u.pm < 32) ? base_lo : base_hi;
; #pragma unroll
;         for (int ai = 0; ai < 2; ++ai) {
;             f32x4 bs[4][2][2];
; #pragma unroll
;             for (int m = 0; m < 4; ++m) { const size_t off = (size_t)(row0 + ai * HALF + m * 16) * DM + col0;
; #pragma unroll
;                 for (int bj = 0; bj < 2; ++bj)
; #pragma unroll
;                     for (int n = 0; n < 2; ++n) bs[m][bj][n] = *(const f32x4*)(base + off + bj * HALF + n * 16); }
; #pragma unroll
;             for (int m = 0; m < 4; ++m) { const size_t off = (size_t)(row0 + ai * HALF + m * 16) * DM + col0;
; #pragma unroll
;                 for (int bj = 0; bj < 2; ++bj)
; #pragma unroll
;                     for (int n = 0; n < 2; ++n) *(f32x4*)(out + off + bj * HALF + n * 16) = bs[m][bj][n] + scale * acc[ai][bj][m][n]; }
; template <class Epi, class Sched>
; __device__ __forceinline__ void gemm_phase(LAS unsigned char* lds, const Gemm g, const Sched& S, const Epi& E) {
;     ...
;         for (int t = 0; t < nt; t += 2) {
;     ...
;             PG8_STAGE(PG8_SB(1, 1), b3 + hstep, voffB);
;             PG8_WAIT_V(6); PG8_BAR; PG8_MMA(1, 1, At, B1); PG8_BAR;
	s_add_u32 s16, s22, 0x80080
	s_addc_u32 s17, s23, 0
	s_add_i32 s22, s24, s31
	s_mov_b32 m0, s22
	s_nop 0
	global_load_lds_dwordx4 v148, s[16:17]
	s_add_i32 m0, s22, 0x2000
	s_nop 0
	global_load_lds_dwordx4 v160, s[16:17]
	s_add_u32 s13, s13, 0x100
	s_addc_u32 s15, s15, 0
	s_cmp_ge_i32 s47, s45
	s_mov_b64 s[16:17], s[20:21]
	s_mov_b32 s22, s47
	s_waitcnt vmcnt(6)
	s_barrier
	v_mfma_f32_16x16x32_bf16 v[44:47], v[220:223], v[144:147], v[44:47]
	v_mfma_f32_16x16x32_bf16 v[40:43], v[228:231], v[144:147], v[40:43]
	v_mfma_f32_16x16x32_bf16 v[28:31], v[220:223], v[170:173], v[28:31]
	v_mfma_f32_16x16x32_bf16 v[24:27], v[228:231], v[170:173], v[24:27]
	v_mfma_f32_16x16x32_bf16 v[12:15], v[220:223], v[204:207], v[12:15]
	v_mfma_f32_16x16x32_bf16 v[8:11], v[228:231], v[204:207], v[8:11]
	v_mfma_f32_16x16x32_bf16 v[4:7], v[220:223], v[212:215], v[4:7]
	v_mfma_f32_16x16x32_bf16 v[0:3], v[228:231], v[212:215], v[0:3]
	v_mfma_f32_16x16x32_bf16 v[44:47], v[224:227], v[166:169], v[44:47]
	v_mfma_f32_16x16x32_bf16 v[40:43], v[232:235], v[166:169], v[40:43]
	v_mfma_f32_16x16x32_bf16 v[28:31], v[224:227], v[174:177], v[28:31]
	v_mfma_f32_16x16x32_bf16 v[24:27], v[232:235], v[174:177], v[24:27]
	v_mfma_f32_16x16x32_bf16 v[12:15], v[224:227], v[208:211], v[12:15]
	v_mfma_f32_16x16x32_bf16 v[8:11], v[232:235], v[208:211], v[8:11]
	v_mfma_f32_16x16x32_bf16 v[4:7], v[224:227], v[216:219], v[4:7]
	v_mfma_f32_16x16x32_bf16 v[0:3], v[232:235], v[216:219], v[0:3]
	s_barrier
	s_cbranch_scc0 .LBB0_267
	v_lshl_add_u32 v166, s46, 8, v200
	v_lshl_or_b32 v168, s44, 8, v202
	s_mov_b64 s[16:17], -1
	s_cmp_lt_i32 s82, 0
	v_ashrrev_i32_e32 v169, 31, v168
	v_ashrrev_i32_e32 v167, 31, v166
	s_cbranch_scc0 .LBB0_270
	v_lshlrev_b64 v[170:171], 2, v[168:169]
	v_lshl_add_u64 v[172:173], s[60:61], 0, v[170:171]
	v_lshlrev_b64 v[174:175], 13, v[166:167]
	v_lshl_add_u64 v[128:129], v[172:173], 0, v[174:175]
	global_load_dwordx4 v[204:207], v[128:129], off
	global_load_dwordx4 v[208:211], v[128:129], off offset:64
	global_load_dwordx4 v[212:215], v[128:129], off offset:512
	global_load_dwordx4 v[216:219], v[128:129], off offset:576
	v_or_b32_e32 v128, 16, v166
	v_ashrrev_i32_e32 v129, 31, v128
	v_lshlrev_b64 v[188:189], 13, v[128:129]
	v_lshl_add_u64 v[128:129], v[172:173], 0, v[188:189]
	global_load_dwordx4 v[220:223], v[128:129], off
	global_load_dwordx4 v[224:227], v[128:129], off offset:64
	global_load_dwordx4 v[228:231], v[128:129], off offset:512
	global_load_dwordx4 v[232:235], v[128:129], off offset:576
	v_or_b32_e32 v128, 32, v166
	v_ashrrev_i32_e32 v129, 31, v128
	v_lshlrev_b64 v[190:191], 13, v[128:129]
	v_lshl_add_u64 v[128:129], v[172:173], 0, v[190:191]
	global_load_dwordx4 v[236:239], v[128:129], off
	global_load_dwordx4 v[240:243], v[128:129], off offset:64
	global_load_dwordx4 v[144:147], v[128:129], off offset:512
	global_load_dwordx4 v[140:143], v[128:129], off offset:576
	v_or_b32_e32 v128, 48, v166
	v_ashrrev_i32_e32 v129, 31, v128
	v_lshlrev_b64 v[176:177], 13, v[128:129]
	v_lshl_add_u64 v[128:129], v[172:173], 0, v[176:177]
	global_load_dwordx4 v[244:247], v[128:129], off
	global_load_dwordx4 v[136:139], v[128:129], off offset:64
	global_load_dwordx4 v[132:135], v[128:129], off offset:512
	s_nop 0
	global_load_dwordx4 v[128:131], v[128:129], off offset:576
	v_lshl_add_u64 v[248:249], s[60:61], 0, v[174:175]
	v_lshl_add_u64 v[248:249], v[248:249], 0, v[170:171]
	v_lshl_add_u64 v[188:189], s[60:61], 0, v[188:189]
	v_lshl_add_u64 v[188:189], v[188:189], 0, v[170:171]
	s_mov_b64 s[16:17], 0x100000
	s_waitcnt vmcnt(0)
	v_pk_add_f32 v[206:207], v[206:207], v[126:127]
	v_pk_add_f32 v[204:205], v[204:205], v[124:125]
	global_store_dwordx4 v[248:249], v[204:207], off
	v_pk_add_f32 v[146:147], v[146:147], v[78:79]
	s_nop 0
	v_pk_add_f32 v[206:207], v[210:211], v[122:123]
	v_pk_add_f32 v[204:205], v[208:209], v[120:121]
	global_store_dwordx4 v[248:249], v[204:207], off offset:64
	v_pk_add_f32 v[144:145], v[144:145], v[76:77]
	v_pk_add_f32 v[142:143], v[142:143], v[74:75]
	v_pk_add_f32 v[206:207], v[214:215], v[110:111]
	v_pk_add_f32 v[204:205], v[212:213], v[108:109]
	global_store_dwordx4 v[248:249], v[204:207], off offset:512
	v_pk_add_f32 v[140:141], v[140:141], v[72:73]
	v_pk_add_f32 v[138:139], v[138:139], v[82:83]
	v_pk_add_f32 v[206:207], v[218:219], v[106:107]
	v_pk_add_f32 v[204:205], v[216:217], v[104:105]
	global_store_dwordx4 v[248:249], v[204:207], off offset:576
	v_pk_add_f32 v[136:137], v[136:137], v[80:81]
	v_pk_add_f32 v[134:135], v[134:135], v[70:71]
	v_pk_add_f32 v[206:207], v[222:223], v[118:119]
	v_pk_add_f32 v[204:205], v[220:221], v[116:117]
	global_store_dwordx4 v[188:189], v[204:207], off
	v_pk_add_f32 v[132:133], v[132:133], v[68:69]
	v_pk_add_f32 v[130:131], v[130:131], v[66:67]
	v_pk_add_f32 v[206:207], v[226:227], v[114:115]
	v_pk_add_f32 v[204:205], v[224:225], v[112:113]
	global_store_dwordx4 v[188:189], v[204:207], off offset:64
	v_pk_add_f32 v[128:129], v[128:129], v[64:65]
	s_nop 0
	v_pk_add_f32 v[206:207], v[230:231], v[94:95]
	v_pk_add_f32 v[204:205], v[228:229], v[92:93]
	global_store_dwordx4 v[188:189], v[204:207], off offset:512
	s_nop 1
	v_pk_add_f32 v[206:207], v[234:235], v[90:91]
	v_pk_add_f32 v[204:205], v[232:233], v[88:89]
	global_store_dwordx4 v[188:189], v[204:207], off offset:576
;     __device__ __forceinline__ void operator()(const f32x4 (&acc)[2][2][4][2], const Unit& u, int wr, int wc, int fr, int fq) const {
;     ...
;         for (int ai = 0; ai < 2; ++ai) {
;             f32x4 bs[4][2][2];
; #pragma unroll
;             for (int m = 0; m < 4; ++m) { const size_t off = (size_t)(row0 + ai * HALF + m * 16) * DM + col0;
; #pragma unroll
;                 for (int bj = 0; bj < 2; ++bj)
; #pragma unroll
;                     for (int n = 0; n < 2; ++n) bs[m][bj][n] = *(const f32x4*)(base + off + bj * HALF + n * 16); }
; #pragma unroll
;             for (int m = 0; m < 4; ++m) { const size_t off = (size_t)(row0 + ai * HALF + m * 16) * DM + col0;
; #pragma unroll
;                 for (int bj = 0; bj < 2; ++bj)
; #pragma unroll
;                     for (int n = 0; n < 2; ++n) *(f32x4*)(out + off + bj * HALF + n * 16) = bs[m][bj][n] + scale * acc[ai][bj][m][n]; }
	v_lshl_add_u64 v[188:189], s[60:61], 0, v[190:191]
	v_lshl_add_u64 v[188:189], v[188:189], 0, v[170:171]
	v_pk_add_f32 v[206:207], v[238:239], v[102:103]
	v_pk_add_f32 v[204:205], v[236:237], v[100:101]
	global_store_dwordx4 v[188:189], v[144:147], off offset:512
	global_store_dwordx4 v[188:189], v[204:207], off
	global_store_dwordx4 v[188:189], v[140:143], off offset:576
	v_lshl_add_u64 v[144:145], s[60:61], 0, v[176:177]
	v_pk_add_f32 v[206:207], v[242:243], v[98:99]
	v_pk_add_f32 v[204:205], v[240:241], v[96:97]
	v_pk_add_f32 v[142:143], v[246:247], v[86:87]
	v_pk_add_f32 v[140:141], v[244:245], v[84:85]
	v_lshl_add_u64 v[144:145], v[144:145], 0, v[170:171]
	global_store_dwordx4 v[188:189], v[204:207], off offset:64
	global_store_dwordx4 v[144:145], v[140:143], off
	global_store_dwordx4 v[144:145], v[136:139], off offset:64
	global_store_dwordx4 v[144:145], v[132:135], off offset:512
	global_store_dwordx4 v[144:145], v[128:131], off offset:576
	v_lshl_add_u64 v[146:147], v[174:175], 0, s[16:17]
	s_mov_b64 s[16:17], 0x120000
	v_lshl_add_u64 v[128:129], v[172:173], 0, v[146:147]
	global_load_dwordx4 v[142:145], v[128:129], off
	global_load_dwordx4 v[204:207], v[128:129], off offset:64
	global_load_dwordx4 v[208:211], v[128:129], off offset:512
	global_load_dwordx4 v[212:215], v[128:129], off offset:576
	v_lshl_add_u64 v[176:177], v[174:175], 0, s[16:17]
	v_lshl_add_u64 v[128:129], v[172:173], 0, v[176:177]
	global_load_dwordx4 v[216:219], v[128:129], off
	global_load_dwordx4 v[220:223], v[128:129], off offset:64
	global_load_dwordx4 v[224:227], v[128:129], off offset:512
	global_load_dwordx4 v[228:231], v[128:129], off offset:576
	s_mov_b64 s[16:17], 0x140000
	v_lshl_add_u64 v[188:189], v[174:175], 0, s[16:17]
	s_mov_b64 s[16:17], 0x160000
	v_lshl_add_u64 v[128:129], v[172:173], 0, v[188:189]
	v_lshl_add_u64 v[140:141], v[174:175], 0, s[16:17]
	global_load_dwordx4 v[232:235], v[128:129], off
	global_load_dwordx4 v[236:239], v[128:129], off offset:64
	global_load_dwordx4 v[240:243], v[128:129], off offset:512
	global_load_dwordx4 v[244:247], v[128:129], off offset:576
	v_lshl_add_u64 v[128:129], v[172:173], 0, v[140:141]
	global_load_dwordx4 v[172:175], v[128:129], off
	global_load_dwordx4 v[136:139], v[128:129], off offset:64
	global_load_dwordx4 v[132:135], v[128:129], off offset:512
	s_nop 0
	global_load_dwordx4 v[128:131], v[128:129], off offset:576
	v_lshl_add_u64 v[146:147], s[60:61], 0, v[146:147]
	v_lshl_add_u64 v[146:147], v[146:147], 0, v[170:171]
	v_lshl_add_u64 v[140:141], s[60:61], 0, v[140:141]
	v_lshl_add_u64 v[140:141], v[140:141], 0, v[170:171]
	s_mov_b64 s[16:17], 0
	s_waitcnt vmcnt(0)
	v_pk_add_f32 v[144:145], v[62:63], v[144:145]
	v_pk_add_f32 v[142:143], v[60:61], v[142:143]
	global_store_dwordx4 v[146:147], v[142:145], off
	v_pk_add_f32 v[138:139], v[18:19], v[138:139]
	s_nop 0
	v_pk_add_f32 v[144:145], v[58:59], v[206:207]
	v_pk_add_f32 v[142:143], v[56:57], v[204:205]
	global_store_dwordx4 v[146:147], v[142:145], off offset:64
	v_pk_add_f32 v[136:137], v[16:17], v[136:137]
	v_pk_add_f32 v[134:135], v[6:7], v[134:135]
	v_pk_add_f32 v[144:145], v[46:47], v[210:211]
	v_pk_add_f32 v[142:143], v[44:45], v[208:209]
	global_store_dwordx4 v[146:147], v[142:145], off offset:512
	v_pk_add_f32 v[132:133], v[4:5], v[132:133]
	v_pk_add_f32 v[130:131], v[2:3], v[130:131]
	v_pk_add_f32 v[144:145], v[42:43], v[214:215]
	v_pk_add_f32 v[142:143], v[40:41], v[212:213]
	global_store_dwordx4 v[146:147], v[142:145], off offset:576
	v_lshl_add_u64 v[146:147], s[60:61], 0, v[176:177]
	v_lshl_add_u64 v[146:147], v[146:147], 0, v[170:171]
	v_pk_add_f32 v[144:145], v[54:55], v[218:219]
	v_pk_add_f32 v[142:143], v[52:53], v[216:217]
	global_store_dwordx4 v[146:147], v[142:145], off
	v_pk_add_f32 v[128:129], v[0:1], v[128:129]
	global_store_dwordx4 v[140:141], v[136:139], off offset:64
	v_pk_add_f32 v[144:145], v[50:51], v[222:223]
	v_pk_add_f32 v[142:143], v[48:49], v[220:221]
	global_store_dwordx4 v[146:147], v[142:145], off offset:64
	global_store_dwordx4 v[140:141], v[132:135], off offset:512
	global_store_dwordx4 v[140:141], v[128:131], off offset:576
	v_pk_add_f32 v[144:145], v[30:31], v[226:227]
	v_pk_add_f32 v[142:143], v[28:29], v[224:225]
	global_store_dwordx4 v[146:147], v[142:145], off offset:512
	s_nop 1
	v_pk_add_f32 v[144:145], v[26:27], v[230:231]
	v_pk_add_f32 v[142:143], v[24:25], v[228:229]
	global_store_dwordx4 v[146:147], v[142:145], off offset:576
	v_lshl_add_u64 v[146:147], s[60:61], 0, v[188:189]
	v_lshl_add_u64 v[146:147], v[146:147], 0, v[170:171]
	v_pk_add_f32 v[144:145], v[38:39], v[234:235]
	v_pk_add_f32 v[142:143], v[36:37], v[232:233]
	global_store_dwordx4 v[146:147], v[142:145], off
	s_nop 1
	v_pk_add_f32 v[144:145], v[34:35], v[238:239]
	v_pk_add_f32 v[142:143], v[32:33], v[236:237]
	global_store_dwordx4 v[146:147], v[142:145], off offset:64
	s_nop 1
	v_pk_add_f32 v[144:145], v[14:15], v[242:243]
	v_pk_add_f32 v[142:143], v[12:13], v[240:241]
	global_store_dwordx4 v[146:147], v[142:145], off offset:512
	s_nop 1
	v_pk_add_f32 v[144:145], v[10:11], v[246:247]
	v_pk_add_f32 v[142:143], v[8:9], v[244:245]
	global_store_dwordx4 v[146:147], v[142:145], off offset:576
	s_nop 1
	v_pk_add_f32 v[144:145], v[22:23], v[174:175]
	v_pk_add_f32 v[142:143], v[20:21], v[172:173]
	global_store_dwordx4 v[140:141], v[142:145], off
